# N1 norm_rows: removed the hipcc vmcnt(3) that split the 8 x-row loads into two serialized batches (sumsq of x0 moved after the counted waits)
# speedup vs baseline: 1.0063x; 1.0063x over previous
; #define p (kparams())
;   __device__ __forceinline__ bool operator()(f32x4 (&acc)[2][2][4][2], const Unit& u, int wr, int wc, int fr, int fq) const {
;     ...
;             if (u.split) { const f32x4 dv = gv[bj][n] * acc[ai][bj][m][n]; float* dp = dst + bj * HALF + n * 16;
;               unsafeAtomicAdd(dp, dv[0]); unsafeAtomicAdd(dp + 1, dv[1]); unsafeAtomicAdd(dp + 2, dv[2]); unsafeAtomicAdd(dp + 3, dv[3]); }
;             else { const f32x4 xi = *(const f32x4*)(src + bj * HALF + n * 16);
;               *(f32x4*)(dst + bj * HALF + n * 16) = xi + gv[bj][n] * acc[ai][bj][m][n]; } } }
; __device__ __forceinline__ void norm_rows(const int wv_, KPR p, int l, int src_layer, const float* gvec, int part_shift, int part_scale, bool copy_ctx) {
;     ...
;   for (int row = blockIdx.x * 8 + wid; row < T; row += gridDim.x * 8) {
;     const float* x = xrow_ptr(p, src_layer, row);
;     const float* mw = modl + (size_t)row_who(row) * 12288;
;     f32x4 v[8]; float ss = 0.f;
; #pragma unroll
;     for (int j = 0; j < 8; ++j) { v[j] = *(const f32x4*)(x + lane * 4 + 256 * j); ss += v[j][0] * v[j][0] + v[j][1] * v[j][1] + v[j][2] * v[j][2] + v[j][3] * v[j][3]; }
;     const float rstd = rsqrtf(wave_sum(ss) * (1.f / D) + 1e-6f);
;     if (copy_ctx && row_who(row) == 4) { float* xd = xrow_dst(p, row);
.LBB0_138:
	s_or_b64 exec, exec, s[20:21]
	v_ashrrev_i32_e32 v5, 31, v4
	v_lshlrev_b64 v[4:5], 13, v[4:5]
	v_lshl_add_u64 v[4:5], v[6:7], 0, v[4:5]
	v_lshlrev_b32_e32 v66, 2, v36
	v_mov_b32_e32 v67, v2
	v_lshl_add_u64 v[4:5], v[4:5], 0, v[66:67]
	global_load_dwordx4 v[32:35], v[4:5], off
	global_load_dwordx4 v[28:31], v[4:5], off offset:1024
	global_load_dwordx4 v[24:27], v[4:5], off offset:2048
	global_load_dwordx4 v[20:23], v[4:5], off offset:3072
	v_add_co_u32_e32 v4, vcc, s52, v4
	s_nop 1
	v_addc_co_u32_e32 v5, vcc, 0, v5, vcc
	global_load_dwordx4 v[16:19], v[4:5], off
	global_load_dwordx4 v[12:15], v[4:5], off offset:1024
	global_load_dwordx4 v[8:11], v[4:5], off offset:2048
	s_nop 0
	global_load_dwordx4 v[4:7], v[4:5], off offset:3072
	v_cmp_eq_u32_e64 s[24:25], 4, v3
	s_nop 3
	s_andn2_b64 s[24:25], s[24:25], s[6:7]
	s_and_b64 vcc, exec, s[24:25]
	s_cbranch_vccz .Lnr_skip
	v_readlane_b32 s24, v242, 62
	s_cmp_lg_u32 s24, 0
	s_cbranch_scc0 .Lnr_skip
	s_add_u32 s22, s16, 0x9ce8000
	s_addc_u32 s23, s17, 0
	s_sub_u32 s20, s14, 0x2000
	s_subb_u32 s21, s15, 0
	v_lshl_add_u32 v222, v1, 8, v37
	v_lshl_add_u32 v222, v222, 13, v66
	v_mov_b32_e32 v223, 0
	v_lshl_add_u64 v[222:223], v[222:223], 0, s[22:23]
	s_mov_b64 s[24:25], 0x1000
	v_lshl_add_u64 v[224:225], v[222:223], 0, s[24:25]
	v_mov_b32_e32 v226, v66
	v_mov_b32_e32 v227, 0
	v_lshl_add_u64 v[226:227], v[226:227], 0, s[20:21]
	v_lshl_add_u64 v[228:229], v[226:227], 0, s[24:25]
	s_mov_b32 s24, 0x800000
	global_load_dwordx4 v[88:91], v[222:223], off
	global_load_dwordx4 v[92:95], v[222:223], off offset:1024
	global_load_dwordx4 v[96:99], v[222:223], off offset:2048
	global_load_dwordx4 v[100:103], v[222:223], off offset:3072
	global_load_dwordx4 v[104:107], v[224:225], off
	global_load_dwordx4 v[108:111], v[224:225], off offset:1024
	global_load_dwordx4 v[112:115], v[224:225], off offset:2048
	global_load_dwordx4 v[116:119], v[224:225], off offset:3072
	v_lshl_add_u64 v[222:223], v[222:223], 0, s[24:25]
	v_lshl_add_u64 v[224:225], v[224:225], 0, s[24:25]
	global_load_dwordx4 v[120:123], v[222:223], off
	global_load_dwordx4 v[124:127], v[222:223], off offset:1024
	global_load_dwordx4 v[128:131], v[222:223], off offset:2048
	global_load_dwordx4 v[132:135], v[222:223], off offset:3072
	global_load_dwordx4 v[136:139], v[224:225], off
	global_load_dwordx4 v[140:143], v[224:225], off offset:1024
	global_load_dwordx4 v[144:147], v[224:225], off offset:2048
	global_load_dwordx4 v[148:151], v[224:225], off offset:3072
	v_lshl_add_u64 v[222:223], v[222:223], 0, s[24:25]
	v_lshl_add_u64 v[224:225], v[224:225], 0, s[24:25]
	global_load_dwordx4 v[190:193], v[222:223], off
	global_load_dwordx4 v[194:197], v[222:223], off offset:1024
	global_load_dwordx4 v[198:201], v[222:223], off offset:2048
	global_load_dwordx4 v[202:205], v[222:223], off offset:3072
	global_load_dwordx4 v[206:209], v[224:225], off
	global_load_dwordx4 v[210:213], v[224:225], off offset:1024
	global_load_dwordx4 v[214:217], v[224:225], off offset:2048
	global_load_dwordx4 v[218:221], v[224:225], off offset:3072
	v_lshl_add_u64 v[222:223], v[222:223], 0, s[24:25]
	v_lshl_add_u64 v[224:225], v[224:225], 0, s[24:25]
	s_waitcnt vmcnt(0)
	v_pk_add_f32 v[88:89], v[88:89], v[120:121]
	v_pk_add_f32 v[90:91], v[90:91], v[122:123]
	v_pk_add_f32 v[92:93], v[92:93], v[124:125]
	v_pk_add_f32 v[94:95], v[94:95], v[126:127]
	v_pk_add_f32 v[96:97], v[96:97], v[128:129]
	v_pk_add_f32 v[98:99], v[98:99], v[130:131]
	v_pk_add_f32 v[100:101], v[100:101], v[132:133]
	v_pk_add_f32 v[102:103], v[102:103], v[134:135]
	v_pk_add_f32 v[104:105], v[104:105], v[136:137]
	v_pk_add_f32 v[106:107], v[106:107], v[138:139]
	v_pk_add_f32 v[108:109], v[108:109], v[140:141]
	v_pk_add_f32 v[110:111], v[110:111], v[142:143]
	v_pk_add_f32 v[112:113], v[112:113], v[144:145]
	v_pk_add_f32 v[114:115], v[114:115], v[146:147]
	v_pk_add_f32 v[116:117], v[116:117], v[148:149]
	v_pk_add_f32 v[118:119], v[118:119], v[150:151]
	v_pk_add_f32 v[88:89], v[88:89], v[190:191]
	v_pk_add_f32 v[90:91], v[90:91], v[192:193]
	v_pk_add_f32 v[92:93], v[92:93], v[194:195]
	v_pk_add_f32 v[94:95], v[94:95], v[196:197]
	v_pk_add_f32 v[96:97], v[96:97], v[198:199]
	v_pk_add_f32 v[98:99], v[98:99], v[200:201]
	v_pk_add_f32 v[100:101], v[100:101], v[202:203]
	v_pk_add_f32 v[102:103], v[102:103], v[204:205]
	v_pk_add_f32 v[104:105], v[104:105], v[206:207]
	v_pk_add_f32 v[106:107], v[106:107], v[208:209]
	v_pk_add_f32 v[108:109], v[108:109], v[210:211]
	v_pk_add_f32 v[110:111], v[110:111], v[212:213]
	v_pk_add_f32 v[112:113], v[112:113], v[214:215]
	v_pk_add_f32 v[114:115], v[114:115], v[216:217]
	v_pk_add_f32 v[116:117], v[116:117], v[218:219]
	v_pk_add_f32 v[118:119], v[118:119], v[220:221]
	global_load_dwordx4 v[120:123], v[222:223], off
	global_load_dwordx4 v[124:127], v[222:223], off offset:1024
	global_load_dwordx4 v[128:131], v[222:223], off offset:2048
	global_load_dwordx4 v[132:135], v[222:223], off offset:3072
	global_load_dwordx4 v[136:139], v[224:225], off
	global_load_dwordx4 v[140:143], v[224:225], off offset:1024
	global_load_dwordx4 v[144:147], v[224:225], off offset:2048
	global_load_dwordx4 v[148:151], v[224:225], off offset:3072
	v_lshl_add_u64 v[222:223], v[222:223], 0, s[24:25]
	v_lshl_add_u64 v[224:225], v[224:225], 0, s[24:25]
	global_load_dwordx4 v[190:193], v[222:223], off
	global_load_dwordx4 v[194:197], v[222:223], off offset:1024
	global_load_dwordx4 v[198:201], v[222:223], off offset:2048
	global_load_dwordx4 v[202:205], v[222:223], off offset:3072
	global_load_dwordx4 v[206:209], v[224:225], off
	global_load_dwordx4 v[210:213], v[224:225], off offset:1024
	global_load_dwordx4 v[214:217], v[224:225], off offset:2048
	global_load_dwordx4 v[218:221], v[224:225], off offset:3072
	v_lshl_add_u64 v[222:223], v[222:223], 0, s[24:25]
	v_lshl_add_u64 v[224:225], v[224:225], 0, s[24:25]
	s_waitcnt vmcnt(0)
; #define p (kparams())
;   __device__ __forceinline__ bool operator()(f32x4 (&acc)[2][2][4][2], const Unit& u, int wr, int wc, int fr, int fq) const {
;     ...
;             if (u.split) { const f32x4 dv = gv[bj][n] * acc[ai][bj][m][n]; float* dp = dst + bj * HALF + n * 16;
;               unsafeAtomicAdd(dp, dv[0]); unsafeAtomicAdd(dp + 1, dv[1]); unsafeAtomicAdd(dp + 2, dv[2]); unsafeAtomicAdd(dp + 3, dv[3]); }
;             else { const f32x4 xi = *(const f32x4*)(src + bj * HALF + n * 16);
;               *(f32x4*)(dst + bj * HALF + n * 16) = xi + gv[bj][n] * acc[ai][bj][m][n]; } } }
; __device__ __forceinline__ void norm_rows(const int wv_, KPR p, int l, int src_layer, const float* gvec, int part_shift, int part_scale, bool copy_ctx) {
;     ...
;     const float* x = xrow_ptr(p, src_layer, row);
;     const float* mw = modl + (size_t)row_who(row) * 12288;
;     f32x4 v[8]; float ss = 0.f;
; #pragma unroll
;     for (int j = 0; j < 8; ++j) { v[j] = *(const f32x4*)(x + lane * 4 + 256 * j); ss += v[j][0] * v[j][0] + v[j][1] * v[j][1] + v[j][2] * v[j][2] + v[j][3] * v[j][3]; }
	v_pk_add_f32 v[88:89], v[88:89], v[120:121]
	v_pk_add_f32 v[90:91], v[90:91], v[122:123]
	v_pk_add_f32 v[92:93], v[92:93], v[124:125]
	v_pk_add_f32 v[94:95], v[94:95], v[126:127]
	v_pk_add_f32 v[96:97], v[96:97], v[128:129]
	v_pk_add_f32 v[98:99], v[98:99], v[130:131]
	v_pk_add_f32 v[100:101], v[100:101], v[132:133]
	v_pk_add_f32 v[102:103], v[102:103], v[134:135]
	v_pk_add_f32 v[104:105], v[104:105], v[136:137]
	v_pk_add_f32 v[106:107], v[106:107], v[138:139]
	v_pk_add_f32 v[108:109], v[108:109], v[140:141]
	v_pk_add_f32 v[110:111], v[110:111], v[142:143]
	v_pk_add_f32 v[112:113], v[112:113], v[144:145]
	v_pk_add_f32 v[114:115], v[114:115], v[146:147]
	v_pk_add_f32 v[116:117], v[116:117], v[148:149]
	v_pk_add_f32 v[118:119], v[118:119], v[150:151]
	v_pk_add_f32 v[88:89], v[88:89], v[190:191]
	v_pk_add_f32 v[90:91], v[90:91], v[192:193]
	v_pk_add_f32 v[92:93], v[92:93], v[194:195]
	v_pk_add_f32 v[94:95], v[94:95], v[196:197]
	v_pk_add_f32 v[96:97], v[96:97], v[198:199]
	v_pk_add_f32 v[98:99], v[98:99], v[200:201]
	v_pk_add_f32 v[100:101], v[100:101], v[202:203]
	v_pk_add_f32 v[102:103], v[102:103], v[204:205]
	v_pk_add_f32 v[104:105], v[104:105], v[206:207]
	v_pk_add_f32 v[106:107], v[106:107], v[208:209]
	v_pk_add_f32 v[108:109], v[108:109], v[210:211]
	v_pk_add_f32 v[110:111], v[110:111], v[212:213]
	v_pk_add_f32 v[112:113], v[112:113], v[214:215]
	v_pk_add_f32 v[114:115], v[114:115], v[216:217]
	v_pk_add_f32 v[116:117], v[116:117], v[218:219]
	v_pk_add_f32 v[118:119], v[118:119], v[220:221]
	global_load_dwordx4 v[120:123], v[222:223], off
	global_load_dwordx4 v[124:127], v[222:223], off offset:1024
	global_load_dwordx4 v[128:131], v[222:223], off offset:2048
	global_load_dwordx4 v[132:135], v[222:223], off offset:3072
	global_load_dwordx4 v[136:139], v[224:225], off
	global_load_dwordx4 v[140:143], v[224:225], off offset:1024
	global_load_dwordx4 v[144:147], v[224:225], off offset:2048
	global_load_dwordx4 v[148:151], v[224:225], off offset:3072
	v_lshl_add_u64 v[222:223], v[222:223], 0, s[24:25]
	v_lshl_add_u64 v[224:225], v[224:225], 0, s[24:25]
	global_load_dwordx4 v[190:193], v[222:223], off
	global_load_dwordx4 v[194:197], v[222:223], off offset:1024
	global_load_dwordx4 v[198:201], v[222:223], off offset:2048
	global_load_dwordx4 v[202:205], v[222:223], off offset:3072
	global_load_dwordx4 v[206:209], v[224:225], off
	global_load_dwordx4 v[210:213], v[224:225], off offset:1024
	global_load_dwordx4 v[214:217], v[224:225], off offset:2048
	global_load_dwordx4 v[218:221], v[224:225], off offset:3072
	v_lshl_add_u64 v[222:223], v[222:223], 0, s[24:25]
	v_lshl_add_u64 v[224:225], v[224:225], 0, s[24:25]
	s_waitcnt vmcnt(0)
	v_pk_add_f32 v[88:89], v[88:89], v[120:121]
	v_pk_add_f32 v[90:91], v[90:91], v[122:123]
	v_pk_add_f32 v[92:93], v[92:93], v[124:125]
	v_pk_add_f32 v[94:95], v[94:95], v[126:127]
	v_pk_add_f32 v[96:97], v[96:97], v[128:129]
	v_pk_add_f32 v[98:99], v[98:99], v[130:131]
	v_pk_add_f32 v[100:101], v[100:101], v[132:133]
	v_pk_add_f32 v[102:103], v[102:103], v[134:135]
	v_pk_add_f32 v[104:105], v[104:105], v[136:137]
	v_pk_add_f32 v[106:107], v[106:107], v[138:139]
	v_pk_add_f32 v[108:109], v[108:109], v[140:141]
	v_pk_add_f32 v[110:111], v[110:111], v[142:143]
	v_pk_add_f32 v[112:113], v[112:113], v[144:145]
	v_pk_add_f32 v[114:115], v[114:115], v[146:147]
	v_pk_add_f32 v[116:117], v[116:117], v[148:149]
	v_pk_add_f32 v[118:119], v[118:119], v[150:151]
	v_pk_add_f32 v[88:89], v[88:89], v[190:191]
	v_pk_add_f32 v[90:91], v[90:91], v[192:193]
	v_pk_add_f32 v[92:93], v[92:93], v[194:195]
	v_pk_add_f32 v[94:95], v[94:95], v[196:197]
	v_pk_add_f32 v[96:97], v[96:97], v[198:199]
	v_pk_add_f32 v[98:99], v[98:99], v[200:201]
	v_pk_add_f32 v[100:101], v[100:101], v[202:203]
	v_pk_add_f32 v[102:103], v[102:103], v[204:205]
	v_pk_add_f32 v[104:105], v[104:105], v[206:207]
	v_pk_add_f32 v[106:107], v[106:107], v[208:209]
	v_pk_add_f32 v[108:109], v[108:109], v[210:211]
	v_pk_add_f32 v[110:111], v[110:111], v[212:213]
	v_pk_add_f32 v[112:113], v[112:113], v[214:215]
	v_pk_add_f32 v[114:115], v[114:115], v[216:217]
	v_pk_add_f32 v[116:117], v[116:117], v[218:219]
	v_pk_add_f32 v[118:119], v[118:119], v[220:221]
	global_load_dwordx4 v[120:123], v[222:223], off
	global_load_dwordx4 v[124:127], v[222:223], off offset:1024
	global_load_dwordx4 v[128:131], v[222:223], off offset:2048
	global_load_dwordx4 v[132:135], v[222:223], off offset:3072
	global_load_dwordx4 v[136:139], v[224:225], off
	global_load_dwordx4 v[140:143], v[224:225], off offset:1024
	global_load_dwordx4 v[144:147], v[224:225], off offset:2048
	global_load_dwordx4 v[148:151], v[224:225], off offset:3072
	global_load_dwordx4 v[190:193], v[226:227], off
	global_load_dwordx4 v[194:197], v[226:227], off offset:1024
	global_load_dwordx4 v[198:201], v[226:227], off offset:2048
	global_load_dwordx4 v[202:205], v[226:227], off offset:3072
	global_load_dwordx4 v[206:209], v[228:229], off
	global_load_dwordx4 v[210:213], v[228:229], off offset:1024
	global_load_dwordx4 v[214:217], v[228:229], off offset:2048
	global_load_dwordx4 v[218:221], v[228:229], off offset:3072
	s_waitcnt vmcnt(0)
	v_pk_add_f32 v[88:89], v[88:89], v[120:121]
	v_pk_add_f32 v[90:91], v[90:91], v[122:123]
	v_pk_add_f32 v[92:93], v[92:93], v[124:125]
	v_pk_add_f32 v[94:95], v[94:95], v[126:127]
	v_pk_add_f32 v[96:97], v[96:97], v[128:129]
	v_pk_add_f32 v[98:99], v[98:99], v[130:131]
	v_pk_add_f32 v[100:101], v[100:101], v[132:133]
	v_pk_add_f32 v[102:103], v[102:103], v[134:135]
	v_pk_add_f32 v[104:105], v[104:105], v[136:137]
	v_pk_add_f32 v[106:107], v[106:107], v[138:139]
	v_pk_add_f32 v[108:109], v[108:109], v[140:141]
	v_pk_add_f32 v[110:111], v[110:111], v[142:143]
	v_pk_add_f32 v[112:113], v[112:113], v[144:145]
	v_pk_add_f32 v[114:115], v[114:115], v[146:147]
	v_pk_add_f32 v[116:117], v[116:117], v[148:149]
	v_pk_add_f32 v[118:119], v[118:119], v[150:151]
	v_pk_fma_f32 v[32:33], v[88:89], v[190:191], v[32:33]
	v_pk_fma_f32 v[34:35], v[90:91], v[192:193], v[34:35]
	v_pk_fma_f32 v[28:29], v[92:93], v[194:195], v[28:29]
	v_pk_fma_f32 v[30:31], v[94:95], v[196:197], v[30:31]
	v_pk_fma_f32 v[24:25], v[96:97], v[198:199], v[24:25]
	v_pk_fma_f32 v[26:27], v[98:99], v[200:201], v[26:27]
	v_pk_fma_f32 v[20:21], v[100:101], v[202:203], v[20:21]
	v_pk_fma_f32 v[22:23], v[102:103], v[204:205], v[22:23]
	v_pk_fma_f32 v[16:17], v[104:105], v[206:207], v[16:17]
	v_pk_fma_f32 v[18:19], v[106:107], v[208:209], v[18:19]
	v_pk_fma_f32 v[12:13], v[108:109], v[210:211], v[12:13]
	v_pk_fma_f32 v[14:15], v[110:111], v[212:213], v[14:15]
	v_pk_fma_f32 v[8:9], v[112:113], v[214:215], v[8:9]
	v_pk_fma_f32 v[10:11], v[114:115], v[216:217], v[10:11]
	v_pk_fma_f32 v[4:5], v[116:117], v[218:219], v[4:5]
	v_pk_fma_f32 v[6:7], v[118:119], v[220:221], v[6:7]
; #define p (kparams())
; __device__ __forceinline__ void norm_rows(const int wv_, KPR p, int l, int src_layer, const float* gvec, int part_shift, int part_scale, bool copy_ctx) {
;     ...
;     f32x4 v[8]; float ss = 0.f;
; #pragma unroll
;     for (int j = 0; j < 8; ++j) { v[j] = *(const f32x4*)(x + lane * 4 + 256 * j); ss += v[j][0] * v[j][0] + v[j][1] * v[j][1] + v[j][2] * v[j][2] + v[j][3] * v[j][3]; }
;     const float rstd = rsqrtf(wave_sum(ss) * (1.f / D) + 1e-6f);
;     if (copy_ctx && row_who(row) == 4) { float* xd = xrow_dst(p, row);
; #pragma unroll
;       for (int j = 0; j < 8; ++j) *(f32x4*)(xd + lane * 4 + 256 * j) = v[j]; }
.Lnr_skip:
	s_waitcnt vmcnt(6)
	v_mul_f32_e32 v53, v33, v33
	v_mul_f32_e32 v55, v29, v29
	s_waitcnt vmcnt(5)
	v_mul_f32_e32 v57, v25, v25
	v_fmac_f32_e32 v53, v32, v32
	v_fmac_f32_e32 v55, v28, v28
	s_waitcnt vmcnt(4)
	v_mul_f32_e32 v59, v21, v21
	v_fmac_f32_e32 v57, v24, v24
	v_fmac_f32_e32 v53, v34, v34
	v_fmac_f32_e32 v55, v30, v30
	v_fmac_f32_e32 v59, v20, v20
	v_fmac_f32_e32 v57, v26, v26
	v_fmac_f32_e32 v53, v35, v35
	v_fmac_f32_e32 v55, v31, v31
	v_fmac_f32_e32 v59, v22, v22
	v_fmac_f32_e32 v57, v27, v27
	v_add_f32_e32 v53, v53, v55
	v_fmac_f32_e32 v59, v23, v23
	v_add_f32_e32 v53, v53, v57
	v_add_f32_e32 v53, v53, v59
	v_cmp_eq_u32_e32 vcc, 4, v3
	s_and_b64 s[22:23], s[6:7], vcc
	s_waitcnt vmcnt(3)
	v_mov_b32_e32 v68, v17
	s_waitcnt vmcnt(2)
	v_mov_b32_e32 v69, v13
	v_mov_b32_e32 v64, v16
	v_mov_b32_e32 v65, v12
	v_pk_mul_f32 v[68:69], v[68:69], v[68:69]
	v_mov_b32_e32 v70, v18
	v_mov_b32_e32 v71, v14
	s_waitcnt vmcnt(1)
	v_mov_b32_e32 v76, v9
	s_waitcnt vmcnt(0)
	v_mov_b32_e32 v77, v5
	v_pk_fma_f32 v[64:65], v[64:65], v[64:65], v[68:69]
	v_mov_b32_e32 v72, v19
	v_mov_b32_e32 v73, v15
	v_mov_b32_e32 v74, v8
	v_mov_b32_e32 v75, v4
	v_pk_mul_f32 v[76:77], v[76:77], v[76:77]
	v_pk_fma_f32 v[64:65], v[70:71], v[70:71], v[64:65]
	v_mov_b32_e32 v78, v10
	v_mov_b32_e32 v79, v6
	v_pk_fma_f32 v[68:69], v[74:75], v[74:75], v[76:77]
	v_pk_fma_f32 v[64:65], v[72:73], v[72:73], v[64:65]
	v_mov_b32_e32 v80, v11
	v_mov_b32_e32 v81, v7
	v_pk_fma_f32 v[68:69], v[78:79], v[78:79], v[68:69]
	v_add_f32_e32 v53, v53, v64
	v_add_f32_e32 v53, v53, v65
	v_pk_fma_f32 v[64:65], v[80:81], v[80:81], v[68:69]
	s_nop 0
	v_add_f32_e32 v53, v53, v64
	v_add_f32_e32 v53, v53, v65
	ds_bpermute_b32 v55, v170, v53
	s_waitcnt lgkmcnt(0)
	v_add_f32_e32 v53, v53, v55
	ds_bpermute_b32 v55, v171, v53
	s_waitcnt lgkmcnt(0)
	v_add_f32_e32 v53, v53, v55
	ds_bpermute_b32 v55, v172, v53
	s_waitcnt lgkmcnt(0)
	v_add_f32_e32 v53, v53, v55
	ds_bpermute_b32 v55, v173, v53
	s_waitcnt lgkmcnt(0)
	v_add_f32_e32 v53, v53, v55
	ds_bpermute_b32 v55, v174, v53
	s_waitcnt lgkmcnt(0)
	v_add_f32_e32 v53, v53, v55
	ds_bpermute_b32 v55, v175, v53
	s_and_saveexec_b64 s[20:21], s[22:23]
	s_cbranch_execz .LBB0_131
	s_and_saveexec_b64 s[24:25], s[4:5]
	s_xor_b64 s[4:5], exec, s[24:25]
	s_load_dwordx2 s[22:23], s[10:11], 0x110
	v_lshl_add_u32 v1, v1, 12, v51
	v_add3_u32 v64, v0, v1, s89
	s_or_saveexec_b64 s[4:5], s[4:5]
	s_waitcnt lgkmcnt(0)
	v_mov_b64_e32 v[68:69], s[22:23]
	s_xor_b64 exec, exec, s[4:5]
	s_cbranch_execz .LBB0_130
	v_lshl_add_u32 v64, v1, 8, v37
	v_mov_b64_e32 v[68:69], s[16:17]
	s_branch .LBB0_130
